# v122 stack plus attention-A (k=5 copy) LDS-DMA issue moved from the loop top into the PV MFMA block
# speedup vs baseline: 1.0009x; 1.0009x over previous
.LBB0_209:
	s_mulk_i32 s21, 0x3c00
	s_mul_hi_u32 s37, s20, 0x3c00
	s_add_i32 s49, s49, 1
	s_add_i32 s37, s37, s21
	s_mulk_i32 s20, 0x3c00
	s_add_u32 s20, s30, s20
	s_addc_u32 s21, s53, s37
	s_lshl_b64 s[42:43], s[42:43], 1
	s_add_u32 s42, s62, s42
	s_addc_u32 s43, s63, s43
	s_lshl_b32 s37, s64, 14
	s_add_i32 s39, s37, 0xffffc000
	s_cmp_lg_u32 s64, 0
	s_cselect_b32 s39, s39, 0x8000
	s_add_i32 s39, s59, s39
	s_add_i32 s100, s37, 0
	s_add_i32 s100, s46, s100
	v_add3_u32 v100, s100, v210, v166
	v_add3_u32 v116, s100, v209, v166
	ds_read_b128 v[88:91], v100
	ds_read_b128 v[92:95], v100 offset:2048
	ds_read_b128 v[96:99], v100 offset:4096
	ds_read_b128 v[100:103], v100 offset:6144
	ds_read_b128 v[104:107], v116
	ds_read_b128 v[108:111], v116 offset:2048
	ds_read_b128 v[112:115], v116 offset:4096
	ds_read_b128 v[116:119], v116 offset:6144
	s_waitcnt lgkmcnt(0)
	v_mfma_f32_16x16x32_bf16 v[120:123], v[88:91], v[4:7], v[16:19]
	v_mfma_f32_16x16x32_bf16 v[88:91], v[88:91], v[12:15], v[20:23]
	v_mfma_f32_16x16x32_bf16 v[124:127], v[92:95], v[4:7], v[16:19]
	v_mfma_f32_16x16x32_bf16 v[92:95], v[92:95], v[12:15], v[20:23]
	v_mfma_f32_16x16x32_bf16 v[128:131], v[96:99], v[4:7], v[16:19]
	v_mfma_f32_16x16x32_bf16 v[96:99], v[96:99], v[12:15], v[20:23]
	v_mfma_f32_16x16x32_bf16 v[132:135], v[100:103], v[4:7], v[16:19]
	v_mfma_f32_16x16x32_bf16 v[100:103], v[100:103], v[12:15], v[20:23]
	v_mfma_f32_16x16x32_bf16 v[172:175], v[104:107], v[8:11], v[88:91]
	s_nop 2
	v_add_u32_e32 v88, s37, v167
	v_mfma_f32_16x16x32_bf16 v[212:215], v[108:111], v[8:11], v[92:95]
	v_add_u32_e32 v89, v88, v210
	ds_read_b128 v[152:155], v89 offset:49152
	s_nop 0
	v_add_u32_e32 v92, v88, v209
	v_mfma_f32_16x16x32_bf16 v[168:171], v[104:107], v[0:3], v[120:123]
	v_mfma_f32_16x16x32_bf16 v[104:107], v[108:111], v[0:3], v[124:127]
	v_mfma_f32_16x16x32_bf16 v[216:219], v[112:115], v[0:3], v[128:131]
	v_mfma_f32_16x16x32_bf16 v[220:223], v[112:115], v[8:11], v[96:99]
	v_mfma_f32_16x16x32_bf16 v[224:227], v[116:119], v[0:3], v[132:135]
	v_mfma_f32_16x16x32_bf16 v[228:231], v[116:119], v[8:11], v[100:103]
	ds_read_b128 v[112:115], v92 offset:49152
	ds_read_b128 v[116:119], v89 offset:51200
	ds_read_b128 v[120:123], v92 offset:51200
	ds_read_b128 v[128:131], v89 offset:53248
	ds_read_b128 v[124:127], v92 offset:53248
	ds_read_b128 v[132:135], v89 offset:55296
	ds_read_b128 v[136:139], v92 offset:55296
	ds_read_b128 v[144:147], v89 offset:57344
	ds_read_b128 v[140:143], v92 offset:57344
	ds_read_b128 v[156:159], v89 offset:59392
	ds_read_b128 v[148:151], v92 offset:59392
	ds_read_b128 v[108:111], v89 offset:61440
	ds_read_b128 v[96:99], v92 offset:61440
	ds_read_b128 v[88:91], v89 offset:63488
	ds_read_b128 v[92:95], v92 offset:63488
	v_exp_f32_e32 v233, v168
	v_exp_f32_e32 v232, v172
	v_exp_f32_e32 v235, v104
	v_exp_f32_e32 v237, v216
	v_exp_f32_e32 v239, v224
	v_exp_f32_e32 v169, v169
	v_exp_f32_e32 v234, v212
	v_exp_f32_e32 v236, v220
	v_exp_f32_e32 v238, v228
	v_exp_f32_e32 v168, v173
	v_exp_f32_e32 v241, v105
	v_exp_f32_e32 v217, v217
	v_exp_f32_e32 v225, v225
	v_exp_f32_e32 v243, v170
	v_exp_f32_e32 v240, v213
	v_exp_f32_e32 v216, v221
	v_exp_f32_e32 v224, v229
	v_exp_f32_e32 v242, v174
	v_exp_f32_e32 v245, v106
	v_exp_f32_e32 v247, v218
	v_exp_f32_e32 v249, v226
	v_exp_f32_e32 v171, v171
	v_exp_f32_e32 v251, v107
	v_exp_f32_e32 v244, v214
	v_exp_f32_e32 v246, v222
	v_exp_f32_e32 v248, v230
	v_exp_f32_e32 v170, v175
	v_exp_f32_e32 v250, v215
	v_exp_f32_e32 v219, v219
	v_exp_f32_e32 v227, v227
	v_exp_f32_e32 v218, v223
	v_exp_f32_e32 v226, v231
	v_pk_add_f32 v[172:173], v[232:233], 0 op_sel_hi:[1,0]
	v_pk_add_f32 v[174:175], v[234:235], 0 op_sel_hi:[1,0]
	v_pk_add_f32 v[212:213], v[236:237], 0 op_sel_hi:[1,0]
	v_pk_add_f32 v[214:215], v[238:239], 0 op_sel_hi:[1,0]
	v_pk_add_f32 v[172:173], v[168:169], v[172:173]
	v_pk_add_f32 v[174:175], v[240:241], v[174:175]
	v_pk_add_f32 v[212:213], v[216:217], v[212:213]
	v_pk_add_f32 v[214:215], v[224:225], v[214:215]
	v_pk_add_f32 v[172:173], v[242:243], v[172:173]
	v_cvt_pk_bf16_f32 v104, v233, v169
	v_cvt_pk_bf16_f32 v105, v243, v171
	v_cvt_pk_bf16_f32 v106, v235, v241
	v_cvt_pk_bf16_f32 v107, v245, v251
	v_pk_add_f32 v[174:175], v[244:245], v[174:175]
	v_pk_add_f32 v[212:213], v[246:247], v[212:213]
	v_pk_add_f32 v[214:215], v[248:249], v[214:215]
	v_pk_add_f32 v[172:173], v[170:171], v[172:173]
	v_cvt_pk_bf16_f32 v168, v232, v168
	v_cvt_pk_bf16_f32 v169, v242, v170
	v_cvt_pk_bf16_f32 v170, v234, v240
	v_cvt_pk_bf16_f32 v171, v244, v250
	v_pk_add_f32 v[174:175], v[250:251], v[174:175]
	v_pk_add_f32 v[212:213], v[218:219], v[212:213]
	v_pk_add_f32 v[214:215], v[226:227], v[214:215]
	s_waitcnt lgkmcnt(0)
	v_mfma_f32_16x16x32_bf16 v[84:87], v[152:155], v[104:107], v[84:87]
	v_add_f32_e64 v172, v172, v174
	v_add_f32_e64 v173, v173, v175
	v_pk_add_f32 v[174:175], v[212:213], v[214:215]
	v_cvt_pk_bf16_f32 v100, v237, v217
	v_mfma_f32_16x16x32_bf16 v[80:83], v[152:155], v[168:171], v[80:83]
	v_add_f32_e64 v172, v172, v174
	v_add_f32_e64 v173, v173, v175
	v_cvt_pk_bf16_f32 v101, v247, v219
	v_cvt_pk_bf16_f32 v102, v239, v225
	v_mfma_f32_16x16x32_bf16 v[76:79], v[116:119], v[104:107], v[76:79]
	v_cvt_pk_bf16_f32 v103, v249, v227
	v_pk_add_f32 v[182:183], v[182:183], v[172:173]
	v_cvt_pk_bf16_f32 v172, v236, v216
	v_mfma_f32_16x16x32_bf16 v[72:75], v[116:119], v[168:171], v[72:75]
	v_cvt_pk_bf16_f32 v173, v246, v218
	v_cvt_pk_bf16_f32 v174, v238, v224
	v_cvt_pk_bf16_f32 v175, v248, v226
	v_mfma_f32_16x16x32_bf16 v[68:71], v[128:131], v[104:107], v[68:71]
	s_add_i32 s101, s64, 1
	s_cmp_lg_u32 s64, 2
	s_cselect_b32 s64, s101, 0
	v_mfma_f32_16x16x32_bf16 v[64:67], v[128:131], v[168:171], v[64:67]
	s_add_u32 s40, s40, 64
	s_addc_u32 s41, s41, 0
	v_mfma_f32_16x16x32_bf16 v[60:63], v[132:135], v[104:107], v[60:63]
	v_mfma_f32_16x16x32_bf16 v[56:59], v[132:135], v[168:171], v[56:59]
	v_lshl_add_u64 v[232:233], v[176:177], 1, s[20:21]
	s_mov_b64 s[4:5], 0x400
	v_lshl_add_u64 v[232:233], v[232:233], 0, s[4:5]
	s_mov_b32 m0, s39
	s_nop 0
	global_load_lds_dwordx4 v[232:233], off
	v_mfma_f32_16x16x32_bf16 v[52:55], v[144:147], v[104:107], v[52:55]
	v_mfma_f32_16x16x32_bf16 v[48:51], v[144:147], v[168:171], v[48:51]
	v_mfma_f32_16x16x32_bf16 v[44:47], v[156:159], v[104:107], v[44:47]
	v_mfma_f32_16x16x32_bf16 v[40:43], v[156:159], v[168:171], v[40:43]
	v_mfma_f32_16x16x32_bf16 v[36:39], v[108:111], v[104:107], v[36:39]
	v_mfma_f32_16x16x32_bf16 v[24:27], v[108:111], v[168:171], v[24:27]
	v_lshl_add_u64 v[232:233], v[160:161], 1, s[42:43]
	s_add_i32 m0, s39, 0xc000
	s_nop 0
	global_load_lds_dwordx4 v[232:233], off
	v_mfma_f32_16x16x32_bf16 v[32:35], v[88:91], v[104:107], v[32:35]
	v_mfma_f32_16x16x32_bf16 v[28:31], v[88:91], v[168:171], v[28:31]
	v_mfma_f32_16x16x32_bf16 v[84:87], v[112:115], v[100:103], v[84:87]
	v_mfma_f32_16x16x32_bf16 v[80:83], v[112:115], v[172:175], v[80:83]
	v_mfma_f32_16x16x32_bf16 v[76:79], v[120:123], v[100:103], v[76:79]
	v_mfma_f32_16x16x32_bf16 v[72:75], v[120:123], v[172:175], v[72:75]
	v_lshl_add_u64 v[232:233], v[162:163], 1, s[20:21]
	v_lshl_add_u64 v[232:233], v[232:233], 0, s[4:5]
	s_add_i32 m0, s39, 0x400
	s_nop 0
	global_load_lds_dwordx4 v[232:233], off
	v_mfma_f32_16x16x32_bf16 v[68:71], v[124:127], v[100:103], v[68:71]
	v_mfma_f32_16x16x32_bf16 v[64:67], v[124:127], v[172:175], v[64:67]
	v_mfma_f32_16x16x32_bf16 v[60:63], v[136:139], v[100:103], v[60:63]
	v_mfma_f32_16x16x32_bf16 v[56:59], v[136:139], v[172:175], v[56:59]
	v_mfma_f32_16x16x32_bf16 v[52:55], v[140:143], v[100:103], v[52:55]
	v_mfma_f32_16x16x32_bf16 v[48:51], v[140:143], v[172:175], v[48:51]
	v_lshl_add_u64 v[232:233], v[164:165], 1, s[42:43]
	s_add_i32 m0, s39, 0xc400
	s_nop 0
	global_load_lds_dwordx4 v[232:233], off
	v_mfma_f32_16x16x32_bf16 v[44:47], v[148:151], v[100:103], v[44:47]
	v_mfma_f32_16x16x32_bf16 v[40:43], v[148:151], v[172:175], v[40:43]
	v_mfma_f32_16x16x32_bf16 v[36:39], v[96:99], v[100:103], v[36:39]
	v_mfma_f32_16x16x32_bf16 v[24:27], v[96:99], v[172:175], v[24:27]
	v_mfma_f32_16x16x32_bf16 v[32:35], v[92:95], v[100:103], v[32:35]
	v_mfma_f32_16x16x32_bf16 v[28:31], v[92:95], v[172:175], v[28:31]
	s_cmp_eq_u32 s49, 34
	s_cbranch_scc1 .LBB0_214
